# hgrn pass 3: q~/k~ LDS tiles stored in a permuted column order so each output-MFMA A fragment is one aligned ds_read_b128 (was two bank-conflicted ds_read2_b64 halves)
# speedup vs baseline: 1.0099x; 1.0099x over previous
.LBB0_395:
	s_or_b64 exec, exec, s[20:21]
	v_readlane_b32 s6, v253, 7
	v_readlane_b32 s7, v253, 8
	s_andn2_b64 vcc, exec, s[6:7]
	s_cbranch_vccnz .LBB0_427
	s_ashr_i32 s5, s4, 6
	s_waitcnt lgkmcnt(0)
	s_add_u32 s38, s16, 0x16000000
	s_addc_u32 s39, s17, 0
	s_ashr_i32 s6, s4, 7
	s_movk_i32 s7, 0x80
	s_mov_b32 s20, s80
	s_add_u32 s15, s16, 0x22000000
	v_cmp_gt_i32_e64 s[40:41], s7, v64
	v_readlane_b32 s7, v253, 37
	v_writelane_b32 v253, s20, 59
	s_addc_u32 s14, s17, 0
	v_lshlrev_b32_e32 v4, 2, v64
	v_writelane_b32 v253, s21, 60
	s_lshl_b32 s20, s5, 4
	s_lshl_b32 s78, s80, 1
	s_ashr_i32 s21, s20, 31
	v_ashrrev_i32_e32 v5, 31, v4
	v_lshlrev_b32_e32 v2, 3, v64
	v_add_u32_e32 v66, s7, v4
	v_lshl_add_u64 v[4:5], v[4:5], 2, s[16:17]
	s_mov_b64 s[22:23], 0x28600000
	v_and_b32_e32 v50, 48, v64
	v_mov_b32_e32 v51, v153
	s_cmp_gt_i32 s6, 0
	v_and_b32_e32 v2, 0x78, v2
	v_lshl_add_u64 v[48:49], v[4:5], 0, s[22:23]
	v_lshl_add_u64 v[4:5], s[16:17], 0, v[50:51]
	s_mov_b64 s[16:17], 0x29600000
	s_cselect_b64 s[42:43], -1, 0
	s_cmp_gt_i32 s6, 1
	v_ashrrev_i32_e32 v65, 4, v64
	v_lshl_add_u64 v[52:53], v[4:5], 0, s[16:17]
	v_lshlrev_b32_e32 v4, 2, v2
	s_cselect_b64 s[44:45], -1, 0
	s_cmp_gt_i32 s6, 2
	v_add_u32_e32 v51, s7, v4
	v_lshl_or_b32 v5, v65, 7, v2
	s_movk_i32 s7, 0x84
	s_cselect_b64 s[46:47], -1, 0
	s_cmp_lt_i32 s6, 3
	v_and_b32_e32 v6, 0x7f, v64
	v_lshl_add_u32 v67, v5, 2, 0
	v_mul_lo_u32 v68, v65, s7
	v_lshlrev_b32_e32 v5, 1, v5
	s_cselect_b64 s[48:49], -1, 0
	s_cmp_lt_i32 s6, 2
	v_lshlrev_b32_e32 v7, 2, v6
	s_waitcnt vmcnt(0)
	v_sub_u32_e32 v8, 0, v5
	v_lshlrev_b32_e32 v5, 2, v68
	v_readlane_b32 s25, v253, 40
	s_cselect_b64 s[50:51], -1, 0
	s_cmp_lt_i32 s6, 1
	v_add_u32_e32 v69, 0, v7
	v_add3_u32 v71, s25, v5, v4
	s_cselect_b64 s[52:53], -1, 0
	s_lshl_b32 s79, s6, 12
	v_lshlrev_b32_e32 v5, 1, v6
	s_lshl_b32 s7, s6, 3
	v_readlane_b32 s24, v253, 38
	s_lshl_b32 s22, s6, 4
	v_sub_u32_e32 v72, v69, v5
	v_and_b32_e32 v166, 0x63, v6
	v_bfe_u32 v167, v6, 2, 2
	v_lshl_or_b32 v166, v167, 3, v166
	v_bfe_u32 v167, v6, 4, 1
	v_lshl_or_b32 v166, v167, 2, v166
	v_lshlrev_b32_e32 v166, 1, v166
	v_mov_b32_e32 v5, s24
	s_movk_i32 s16, 0x50
	s_cmp_lt_u32 s5, 2
	v_mad_u32_u24 v9, v6, s16, v5
	s_cselect_b64 s[68:69], -1, 0
	v_readlane_b32 s16, v253, 39
	s_cmp_lt_i32 s5, 3
	v_and_b32_e32 v0, 15, v64
	v_add_u32_e32 v73, s16, v7
	s_cselect_b64 s[16:17], -1, 0
	s_cmp_gt_i32 s5, 0
	s_cselect_b32 s23, 16, 0
	s_cmp_eq_u32 s5, 2
	v_or_b32_e32 v5, s23, v0
	v_mul_u32_u24_e32 v5, 0x110, v5
	s_cselect_b32 s5, 16, 0
	v_add3_u32 v74, 0, v5, v50
	v_or_b32_e32 v5, s5, v0
	s_movk_i32 s5, 0x210
	v_mul_lo_u32 v12, v65, s5
	s_or_b32 s5, s7, 1
	s_lshl_b32 s80, s6, 11
	s_mulk_i32 s6, 0x880
	s_lshl_b32 s81, s5, 8
	s_mulk_i32 s5, 0x110
	v_add_u32_e32 v81, s6, v166
	s_add_i32 s6, s5, 0x110
	v_add_u32_e32 v83, s6, v166
	s_add_i32 s6, s5, 0x220
	v_add_u32_e32 v84, s6, v166
	s_add_i32 s6, s5, 0x330
	v_bfe_u32 v3, v64, 4, 2
	v_lshlrev_b32_e32 v152, 1, v2
	v_add_u32_e32 v85, s6, v166
	s_add_i32 s6, s5, 0x440
	s_andn2_b32 s4, s4, 63
	v_lshl_add_u64 v[54:55], s[38:39], 0, v[152:153]
	v_mul_u32_u24_e32 v76, 0x840, v3
	v_add_u32_e32 v82, s5, v166
	v_add_u32_e32 v86, s6, v166
	s_add_i32 s6, s5, 0x550
	s_addk_i32 s5, 0x660
	s_add_i32 s4, s4, s25
	v_lshlrev_b32_e32 v152, 2, v0
	v_add_u32_e32 v79, s24, v50
	v_add3_u32 v80, s25, v12, v4
	v_add_u32_e32 v88, s5, v166
	v_add3_u32 v90, s4, v76, v152
	s_load_dwordx2 s[24:25], s[0:1], 0x50
	s_load_dwordx2 s[4:5], s[0:1], 0x10
	v_mul_u32_u24_e32 v7, 0x110, v5
	v_add3_u32 v75, 0, v7, v50
	v_lshl_or_b32 v7, v3, 2, s23
	v_mul_u32_u24_e32 v77, 0x50, v0
	v_or_b32_e32 v4, 1, v7
	v_lshl_add_u32 v10, v5, 1, s87
	v_add3_u32 v78, s87, v77, v50
	s_or_b32 s82, s80, 0x200
	s_or_b32 s83, s80, 0x300
	s_or_b32 s84, s80, 0x400
	s_or_b32 s85, s80, 0x500
	s_or_b32 s86, s80, 0x600
	v_add_u32_e32 v87, s6, v166
	s_or_b32 s87, s80, 0x700
	v_cmp_gt_u32_e64 s[56:57], v5, v4
	v_or_b32_e32 v4, 2, v7
	s_lshl_b64 s[6:7], s[20:21], 2
	v_and_b32_e32 v1, 63, v64
	v_cmp_gt_u32_e64 s[58:59], v5, v4
	v_or_b32_e32 v4, 3, v7
	s_waitcnt lgkmcnt(0)
	s_add_u32 s4, s4, s6
	v_lshlrev_b32_e32 v6, 3, v3
	v_mul_u32_u24_e32 v11, 0x110, v0
	v_cmp_gt_u32_e64 s[60:61], v5, v4
	v_or_b32_e32 v4, 48, v1
	s_addc_u32 s5, s5, s7
	v_cmp_gt_u32_e64 s[54:55], v5, v7
	v_add3_u32 v89, 0, v11, v6
	v_mul_u32_u24_e32 v11, 0x50, v4
	v_lshl_add_u64 v[4:5], s[4:5], 0, v[152:153]
	s_load_dwordx2 s[4:5], s[0:1], 0x88
	v_mul_u32_u24_e32 v12, 0x50, v7
	v_or_b32_e32 v1, 0x70, v1
	v_mul_u32_u24_e32 v1, 0x50, v1
	v_subrev_u32_e32 v70, 32, v65
	s_waitcnt lgkmcnt(0)
	s_add_u32 s4, s4, s6
	s_addc_u32 s5, s5, s7
	v_lshl_add_u64 v[6:7], s[4:5], 0, v[152:153]
	v_lshlrev_b32_e32 v152, 11, v3
	v_lshl_add_u64 v[56:57], v[4:5], 0, v[152:153]
	v_lshl_add_u64 v[4:5], v[6:7], 0, v[152:153]
	s_mov_b64 s[4:5], 0x6000000
	v_lshl_add_u64 v[58:59], v[4:5], 0, s[4:5]
	v_add_u32_e32 v91, 32, v65
	v_sub_u32_e32 v92, 0xffffffdf, v65
	v_lshlrev_b32_e32 v152, 1, v2
	v_add_u32_e32 v93, v67, v8
	v_add_u32_e32 v94, s22, v9
	v_add_u32_e32 v95, v10, v12
	s_lshl_b32 s88, s20, 1
	v_lshlrev_b32_e32 v96, 1, v0
	v_add_u32_e32 v97, v79, v11
	v_add_u32_e32 v98, v79, v1
	s_mov_b32 s89, s2
	s_branch .LBB0_398

.LBB0_415:
	s_add_i32 s4, s88, s4
	s_waitcnt lgkmcnt(0)
	s_barrier
	v_add3_u32 v47, s4, v76, v96
	ds_read_u16 v166, v47
	ds_read_u16 v167, v47 offset:264
	ds_read_u16 v168, v47 offset:528
	ds_read_u16 v169, v47 offset:792
	ds_read_u16 v170, v47 offset:1056
	ds_read_u16 v171, v47 offset:1320
	ds_read_u16 v172, v47 offset:1584
	ds_read_u16 v173, v47 offset:1848
	v_lshrrev_b32_e32 v122, 1, v50
	v_add_u32_e32 v101, v89, v122
	ds_read_b128 v[174:177], v101 offset:49152
	ds_read_b128 v[178:181], v101 offset:53504
	ds_read_b128 v[182:185], v101 offset:49216
	ds_read_b128 v[186:189], v101 offset:53568
	s_add_i32 s6, s6, 1
	s_add_i32 s4, s5, s6
	v_add_u32_e32 v99, 32, v99
	v_subrev_u32_e32 v100, 32, v100
	v_add_u32_e32 v251, 0x18600, v50
	v_add_u32_e32 v250, v79, v77
	s_cmp_eq_u32 s4, 1
	v_cvt_pk_bf16_f32 v110, v16, v17
	v_cvt_pk_bf16_f32 v111, v18, v19
	v_cvt_pk_bf16_f32 v112, v12, v13
	v_cvt_pk_bf16_f32 v113, v14, v15
	s_waitcnt lgkmcnt(4)
	v_lshl_or_b32 v44, v167, 16, v166
	v_lshl_or_b32 v45, v169, 16, v168
	v_lshl_or_b32 v46, v171, 16, v170
	v_lshl_or_b32 v47, v173, 16, v172
	ds_read_b128 v[190:193], v101 offset:49280
	ds_read_b128 v[206:209], v101 offset:53632
	ds_read_b128 v[210:213], v101 offset:49344
	ds_read_b128 v[214:217], v101 offset:53696
	ds_read_b128 v[218:221], v78
	ds_read_b128 v[222:225], v78 offset:1280
	s_waitcnt lgkmcnt(9)
	v_mfma_f32_16x16x32_bf16 v[106:109], v[174:177], v[110:113], 0
	s_waitcnt lgkmcnt(8)
	v_mfma_f32_16x16x32_bf16 v[102:105], v[178:181], v[110:113], 0
	v_cvt_pk_bf16_f32 v110, v24, v25
	v_cvt_pk_bf16_f32 v111, v26, v27
	v_cvt_pk_bf16_f32 v112, v20, v21
	v_cvt_pk_bf16_f32 v113, v22, v23
	ds_read_b128 v[226:229], v251
	ds_read_b128 v[230:233], v251 offset:64
	ds_read_b128 v[234:237], v251 offset:128
	ds_read_b128 v[238:241], v251 offset:192
	s_waitcnt lgkmcnt(11)
	v_mfma_f32_16x16x32_bf16 v[106:109], v[182:185], v[110:113], v[106:109]
	s_waitcnt lgkmcnt(10)
	v_mfma_f32_16x16x32_bf16 v[102:105], v[186:189], v[110:113], v[102:105]
	v_cvt_pk_bf16_f32 v110, v32, v33
	v_cvt_pk_bf16_f32 v111, v34, v35
	v_cvt_pk_bf16_f32 v112, v28, v29
	v_cvt_pk_bf16_f32 v113, v30, v31
	ds_read_b128 v[242:245], v251 offset:256
	ds_read_b128 v[246:249], v251 offset:320
	ds_read_b128 v[114:117], v251 offset:384
	ds_read_b128 v[118:121], v251 offset:448
	s_waitcnt lgkmcnt(13)
	v_mfma_f32_16x16x32_bf16 v[106:109], v[190:193], v[110:113], v[106:109]
	s_waitcnt lgkmcnt(12)
	v_mfma_f32_16x16x32_bf16 v[102:105], v[206:209], v[110:113], v[102:105]
	v_cvt_pk_bf16_f32 v110, v36, v37
	v_cvt_pk_bf16_f32 v111, v38, v39
	v_cvt_pk_bf16_f32 v112, v40, v41
	v_cvt_pk_bf16_f32 v113, v42, v43
	ds_read_b128 v[174:177], v250
	ds_read_b128 v[178:181], v250 offset:1280
	s_waitcnt lgkmcnt(13)
	v_mfma_f32_16x16x32_bf16 v[106:109], v[210:213], v[110:113], v[106:109]
	s_waitcnt lgkmcnt(12)
	v_mfma_f32_16x16x32_bf16 v[102:105], v[214:217], v[110:113], v[102:105]
	ds_read_b128 v[182:185], v250 offset:2560
	ds_read_b128 v[186:189], v97
	s_waitcnt lgkmcnt(12)
	v_mfma_f32_16x16x32_bf16 v[102:105], v[222:225], v[44:47], v[102:105]
	v_mfma_f32_16x16x32_bf16 v[106:109], v[218:221], v[44:47], v[106:109]
	ds_read_b128 v[190:193], v250 offset:5120
	ds_read_b128 v[206:209], v250 offset:6400
	s_waitcnt lgkmcnt(5)
	v_pk_mul_f32 v[16:17], v[16:17], v[226:227]
	v_pk_mul_f32 v[18:19], v[18:19], v[228:229]
	ds_read_b128 v[210:213], v250 offset:7680
	ds_read_b128 v[214:217], v98
	v_mfma_f32_16x16x32_bf16 v[16:19], v[174:177], v[44:47], v[16:19]
	s_waitcnt lgkmcnt(6)
	v_pk_mul_f32 v[12:13], v[12:13], v[230:231]
	v_pk_mul_f32 v[14:15], v[14:15], v[232:233]
	v_add_u32_e32 v205, 0x2000, v90
	v_add_u32_e32 v250, 0x400, v90
	v_add_u32_e32 v251, 0x2400, v90
	v_mfma_f32_16x16x32_bf16 v[12:15], v[178:181], v[44:47], v[12:15]
	ds_write2_b32 v205, v102, v103 offset0:64 offset1:196
	ds_write2_b32 v250, v108, v109 offset0:8 offset1:140
	ds_write2_b32 v251, v104, v105 offset0:72 offset1:204
	ds_write2_b32 v90, v106, v107 offset1:132
	s_waitcnt lgkmcnt(9)
	v_pk_mul_f32 v[24:25], v[24:25], v[234:235]
	v_pk_mul_f32 v[26:27], v[26:27], v[236:237]
	s_nop 1
	v_mfma_f32_16x16x32_bf16 v[24:27], v[182:185], v[44:47], v[24:27]
	s_waitcnt lgkmcnt(8)
	v_pk_mul_f32 v[20:21], v[20:21], v[238:239]
	v_pk_mul_f32 v[22:23], v[22:23], v[240:241]
	s_nop 1
	v_mfma_f32_16x16x32_bf16 v[20:23], v[186:189], v[44:47], v[20:23]
	s_waitcnt lgkmcnt(7)
	v_pk_mul_f32 v[32:33], v[32:33], v[242:243]
	v_pk_mul_f32 v[34:35], v[34:35], v[244:245]
	s_nop 1
	v_mfma_f32_16x16x32_bf16 v[32:35], v[190:193], v[44:47], v[32:35]
	s_waitcnt lgkmcnt(6)
	v_pk_mul_f32 v[28:29], v[28:29], v[246:247]
	v_pk_mul_f32 v[30:31], v[30:31], v[248:249]
	s_nop 1
	v_mfma_f32_16x16x32_bf16 v[28:31], v[206:209], v[44:47], v[28:31]
	s_waitcnt lgkmcnt(5)
	v_pk_mul_f32 v[36:37], v[36:37], v[114:115]
	v_pk_mul_f32 v[38:39], v[38:39], v[116:117]
	s_nop 1
	v_mfma_f32_16x16x32_bf16 v[36:39], v[210:213], v[44:47], v[36:39]
	s_waitcnt lgkmcnt(0)
	v_pk_mul_f32 v[40:41], v[40:41], v[118:119]
	v_pk_mul_f32 v[42:43], v[42:43], v[120:121]
	s_nop 1
	v_mfma_f32_16x16x32_bf16 v[40:43], v[214:217], v[44:47], v[40:43]
	s_cbranch_scc1 .LBB0_424
